# scan: kd-transpose fragments read as 8-byte halves (zero pads kept in registers) from a slot-swizzled image
# speedup vs baseline: 1.0100x; 1.0005x over previous
; __device__ __forceinline__ int opaque_tid() { int t = threadIdx.x; asm volatile("" : "+v"(t)); return t; }
; __device__ __forceinline__ void scan_phase(LAS unsigned char* lds, bf16* proj, int G, int bid) {
;     const int tid = opaque_tid(), lane = tid & 63, wave = tid >> 6, fr = lane & 15, fq = lane >> 4;
;     constexpr int KRS = 132;
;     constexpr int SET = 34304, O_KR = 0, O_QR = 8448, O_QE = 16896, O_KE = 21248, O_KD = 25600, O_DV = 33792, O_VT = 2 * SET, QST = 272;
;     const int st = tid >> 4, sc8 = tid & 15;
;     const int pdk = tid >> 2, ptq = tid & 3;
;     const bool stager = tid < 256;
;     ...
;     for (int chain = bid; chain < 256; chain += G) {
;         const int b = chain >> 4, h = (chain >> 1) & 7, dir = chain & 1;
;         const int kcol = 1024 + dir * 1024 + h * 128;
;         f32x4 S[8];
; #pragma unroll
;         for (int i = 0; i < 8; ++i) S[i] = (f32x4){0.f, 0.f, 0.f, 0.f};
;         u32x4 rk = (u32x4){0u, 0u, 0u, 0u}, rq = rk, rv = rk;
.LBB0_413:
	s_or_b64 exec, exec, s[0:1]
	v_readlane_b32 s0, v255, 33
	v_readlane_b32 s1, v255, 34
	s_xor_b64 s[0:1], s[0:1], -1
	v_writelane_b32 v255, s0, 46
	s_waitcnt lgkmcnt(0)
	s_barrier
	v_writelane_b32 v255, s1, 47
	s_nop 0
	v_readlane_b32 s0, v255, 39
	v_readlane_b32 s1, v255, 40
	s_and_b64 vcc, exec, s[0:1]
	s_mov_b64 s[0:1], -1
	s_cbranch_vccnz .LBB0_592
	v_readlane_b32 s4, v254, 43
	v_readlane_b32 s5, v254, 44
	s_and_b64 vcc, exec, s[4:5]
	s_cbranch_vccz .LBB0_496
	v_readlane_b32 s0, v253, 62
	v_readlane_b32 s1, v253, 63
	s_mov_b64 s[24:25], s[42:43]
	v_mov_b32_e32 v0, v209
	s_andn2_b64 vcc, exec, s[0:1]
	s_cbranch_vccnz .LBB0_444
	s_movk_i32 s0, 0x100
	v_ashrrev_i32_e32 v71, 2, v0
	v_cmp_gt_i32_e64 s[38:39], s0, v0
	s_movk_i32 s0, 0x200
	v_ashrrev_i32_e32 v70, 4, v0
	v_lshlrev_b32_e32 v72, 1, v71
	v_cmp_gt_i32_e64 s[42:43], s0, v0
	s_movk_i32 s0, 0x84
	v_and_b32_e32 v53, 15, v0
	v_add_u32_e32 v1, 0, v72
	s_waitcnt vmcnt(2)
	v_mul_lo_u32 v6, v70, s0
	v_add_u32_e32 v4, v1, v72
	v_bfe_u32 v5, v0, 4, 2
	v_lshlrev_b32_e32 v75, 2, v6
	v_lshlrev_b32_e32 v6, 5, v53
	s_waitcnt vmcnt(0)
	v_ashrrev_i32_e32 v8, 3, v0
	v_add3_u32 v76, 0, v75, v6
	v_lshlrev_b32_e32 v6, 9, v53
	v_readlane_b32 s4, v254, 11
	v_lshlrev_b32_e32 v8, 1, v8
	v_lshlrev_b32_e32 v9, 1, v70
	v_mad_u64_u32 v[54:55], s[0:1], v71, 60, v[4:5]
	v_and_b32_e32 v3, 3, v0
	v_add_u32_e32 v7, s4, v6
	v_and_b32_e32 v8, -16, v8
	v_and_b32_e32 v9, 6, v9
	s_movk_i32 s0, 0xffc4
	v_add3_u32 v77, v7, v8, v9
	v_mul_u32_u24_e32 v80, 0x210, v3
	v_mul_u32_u24_e32 v7, 0x220, v3
	v_mul_lo_u32 v84, v71, s0
	v_readlane_b32 s0, v254, 12
	v_lshl_add_u32 v81, v80, 2, v4
	v_lshl_add_u32 v82, v7, 1, v1
	v_and_b32_e32 v206, 12, v71
	v_lshlrev_b32_e32 v206, 1, v206
	v_bfe_u32 v207, v71, 4, 1
	v_lshl_or_b32 v206, v207, 2, v206
	v_and_b32_e32 v207, 3, v71
	v_or_b32_e32 v206, v206, v207
	v_and_b32_e32 v207, 0xffffffe0, v71
	v_or_b32_e32 v206, v206, v207
	v_lshlrev_b32_e32 v206, 1, v206
	v_sub_u32_e32 v82, v82, v72
	v_add_u32_e32 v82, v82, v206
	v_add_u32_e32 v1, s0, v6
	v_and_b32_e32 v4, -16, v71
	v_add3_u32 v85, v1, v8, v9
	v_and_b32_e32 v204, 3, v53
	v_lshlrev_b32_e32 v204, 4, v204
	v_xor_b32_e32 v77, v77, v204
	v_xor_b32_e32 v85, v85, v204
	v_bfe_u32 v204, v53, 2, 1
	v_lshlrev_b32_e32 v204, 6, v204
	v_sub_u32_e32 v180, v77, v204
	v_sub_u32_e32 v181, v85, v204
	v_add_u32_e32 v77, v77, v204
	v_add_u32_e32 v85, v85, v204
	v_lshlrev_b32_e32 v89, 4, v5
	v_lshlrev_b32_e32 v56, 3, v5
	v_lshlrev_b32_e32 v1, 2, v5
	v_ashrrev_i32_e32 v5, 31, v4
	v_lshl_add_u64 v[4:5], v[4:5], 1, s[82:83]
	v_mov_b32_e32 v57, v2
	v_lshlrev_b32_e32 v83, 6, v71
	v_lshl_add_u64 v[58:59], v[4:5], 0, v[56:57]
	v_lshlrev_b32_e32 v4, 4, v53
	v_mov_b32_e32 v5, v2
	s_movk_i32 s0, 0x10ff
	v_cmp_lt_i32_e64 s[40:41], s22, v0
	v_lshlrev_b32_e32 v73, 4, v0
	v_lshl_add_u64 v[60:61], s[82:83], 0, v[4:5]
	v_lshlrev_b32_e32 v57, 6, v53
	v_cmp_gt_u32_e64 s[48:49], v1, v53
	v_cmp_lt_u32_e64 s[50:51], v1, v53
	v_or_b32_e32 v4, 2, v1
	v_or_b32_e32 v1, 3, v1
	v_bitop3_b32 v92, v0, s0, 15 bitop3:0x6c
	v_and_b32_e32 v0, 0xfffffc00, v83
	v_cmp_gt_u32_e64 s[54:55], v1, v53
	v_lshlrev_b32_e32 v1, 10, v3
	v_or3_b32 v0, v0, v57, v89
	v_sub_u32_e32 v74, 0xff, v70
	v_lshlrev_b32_e32 v52, 3, v53
	v_add_u32_e32 v78, 16, v70
	v_sub_u32_e32 v79, 0xef, v70
	v_cmp_eq_u32_e64 s[44:45], 0, v3
	v_cmp_lt_u32_e64 s[46:47], 1, v3
	v_lshlrev_b32_e32 v55, 4, v3
	v_bfe_u32 v208, v209, 4, 2
	v_sub_u32_e32 v208, 0, v208
	v_and_b32_e32 v208, 3, v208
	v_lshlrev_b32_e32 v208, 4, v208
	v_xor_b32_e32 v55, v55, v208
	v_bfe_u32 v210, v209, 2, 2
	v_sub_u32_e32 v210, 0, v210
	v_and_b32_e32 v210, 3, v210
	v_bfe_u32 v212, v209, 4, 2
	v_xor_b32_e32 v210, v210, v212
	v_sub_u32_e32 v210, v210, v212
	v_lshlrev_b32_e32 v210, 4, v210
	v_add_u32_e32 v210, v210, v57
	v_add_u32_e32 v86, 32, v70
	v_sub_u32_e32 v87, 0xdf, v70
	v_mul_u32_u24_e32 v88, 0x110, v53
	v_cmp_gt_u32_e64 s[52:53], v4, v53
	v_sub_u32_e32 v90, 0, v1
	v_sub_u32_e32 v91, 0, v70
	v_lshrrev_b32_e32 v204, 5, v0
	v_and_b32_e32 v204, 0x70, v204
	v_xor_b32_e32 v0, v0, v204
	v_add_u32_e32 v93, s4, v0
	s_mov_b32 s13, s2
	s_branch .LBB0_418

; #define LAS __attribute__((address_space(3)))
; #define SC_LOAD(c_) do { const bf16* rp_ = proj + (size_t)scan_row16(b, dir, (c_), st) * HIN + h * 128 + sc8 * 8; \
;         rq = *(const u32x4*)rp_; rk = *(const u32x4*)(rp_ + kcol - h * 128); rv = *(const u32x4*)(rp_ + 3072); } while (0)
; __device__ __forceinline__ void scan_phase(LAS unsigned char* lds, bf16* proj, int G, int bid) {
;     ...
;         const int b = chain >> 4, h = (chain >> 1) & 7, dir = chain & 1;
;         const int kcol = 1024 + dir * 1024 + h * 128;
;         f32x4 S[8];
; #pragma unroll
;         for (int i = 0; i < 8; ++i) S[i] = (f32x4){0.f, 0.f, 0.f, 0.f};
;         u32x4 rk = (u32x4){0u, 0u, 0u, 0u}, rq = rk, rv = rk;
;     ...
;         __syncthreads();
;         {
;             const u32x4 z4 = (u32x4){0u, 0u, 0u, 0u};
;             for (int o_ = tid * 16; o_ < 8192; o_ += NTHR * 16) { *(LAS u32x4*)(lds + O_KD + o_) = z4; *(LAS u32x4*)(lds + SET + O_KD + o_) = z4; *(LAS u32x4*)(lds + O_VT + o_) = z4; *(LAS u32x4*)(lds + O_VT + 8192 + o_) = z4; *(LAS u32x4*)(lds + O_VT + 16384 + o_) = z4; }
;         }
;         if (stager) SC_LOAD(0);
;         __syncthreads();
;         if (stager) { SC_WRITE(0); SC_LOAD(1); }
;         __syncthreads();
;         SC_PREP(0);
;         if (stager) { SC_WRITE(1); SC_LOAD(2); }
;         __syncthreads();
; #pragma unroll 1
.LBB0_431:
	s_or_b64 exec, exec, s[4:5]
	s_cmp_eq_u32 s15, 0
	v_lshlrev_b32_e32 v64, 1, v18
	v_mov_b32_e32 v65, v2
	v_lshlrev_b32_e32 v0, 1, v0
	v_mov_b32_e32 v1, v2
	v_mov_b32_e32 v44, 0
	s_mov_b32 s4, 0
	s_cselect_b64 s[56:57], -1, 0
	v_lshl_add_u64 v[66:67], v[58:59], 0, v[64:65]
	s_lshl_b32 s5, s14, 12
	v_lshl_add_u64 v[68:69], v[60:61], 0, v[0:1]
	v_mov_b32_e32 v95, v93
	v_mov_b32_e32 v96, v92
	v_mov_b32_e32 v97, v91
	s_mov_b32 s6, 0
	v_mov_b32_e32 v45, v44
	v_mov_b32_e32 v46, v44
	v_mov_b32_e32 v47, v44
	v_mov_b32_e32 v16, v44
	v_mov_b32_e32 v17, v44
	v_mov_b32_e32 v18, v44
	v_mov_b32_e32 v19, v44
	v_mov_b32_e32 v20, v44
	v_mov_b32_e32 v21, v44
	v_mov_b32_e32 v22, v44
	v_mov_b32_e32 v23, v44
	v_mov_b32_e32 v24, v44
	v_mov_b32_e32 v25, v44
	v_mov_b32_e32 v26, v44
	v_mov_b32_e32 v27, v44
	v_mov_b32_e32 v28, v44
	v_mov_b32_e32 v29, v44
	v_mov_b32_e32 v30, v44
	v_mov_b32_e32 v31, v44
	v_mov_b32_e32 v32, v44
	v_mov_b32_e32 v33, v44
	v_mov_b32_e32 v34, v44
	v_mov_b32_e32 v35, v44
	v_mov_b32_e32 v36, v44
	v_mov_b32_e32 v37, v44
	v_mov_b32_e32 v38, v44
	v_mov_b32_e32 v39, v44
	v_mov_b32_e32 v40, v44
	v_mov_b32_e32 v41, v44
	v_mov_b32_e32 v42, v44
	v_mov_b32_e32 v43, v44
	v_mov_b32_e32 v186, v44
	v_mov_b32_e32 v187, v44
	v_mov_b32_e32 v190, v44
	v_mov_b32_e32 v191, v44
	v_mov_b32_e32 v194, v44
	v_mov_b32_e32 v195, v44
	v_mov_b32_e32 v198, v44
	v_mov_b32_e32 v199, v44
	v_mov_b32_e32 v202, v44
	v_mov_b32_e32 v203, v44
	v_mov_b32_e32 v226, v44
	v_mov_b32_e32 v227, v44
	v_mov_b32_e32 v230, v44
	v_mov_b32_e32 v231, v44
	v_mov_b32_e32 v234, v44
	v_mov_b32_e32 v235, v44
	s_waitcnt lgkmcnt(0)
	s_barrier
	s_branch .LBB0_433

; #define LAS __attribute__((address_space(3)))
; __device__ __forceinline__ void scan_phase(LAS unsigned char* lds, bf16* proj, int G, int bid) {
;     ...
;                 const LAS unsigned char* qeb = set + O_QE + fr * QST; const LAS unsigned char* keb = set + O_KE + fr * QST;
;                 bf16x8 kaf[4], qbf[4];
; #pragma unroll
;                 for (int i = 0; i < 4; ++i) { kaf[i] = *(const LAS bf16x8*)(keb + (32 * i + fq * 8) * 2); qbf[i] = *(const LAS bf16x8*)(qeb + (32 * i + fq * 8) * 2); }
;                 u32x2 qlo[4], qhi[4];
; #pragma unroll
;                 for (int i = 0; i < 4; ++i) { qlo[i] = *(const LAS u32x2*)(qeb + (32 * i + fq * 4) * 2); qhi[i] = *(const LAS u32x2*)(qeb + (32 * i + 16 + fq * 4) * 2); }
;                 const bf16x8 vf = *(const LAS bf16x8*)(lds + O_VT + (c % 3) * 8192 + (wave * 16 + fr) * 64 + fq * 16);
;                 f32x4 pt = (f32x4){0.f, 0.f, 0.f, 0.f};
;                 __builtin_amdgcn_s_setprio(1);
; #pragma unroll
;                 for (int i = 0; i < 4; ++i) pt = __builtin_amdgcn_mfma_f32_16x16x32_bf16(kaf[i], qbf[i], pt, 0, 0, 0);
;                 f32x4 oacc = (f32x4){0.f, 0.f, 0.f, 0.f};
; #pragma unroll
;                 for (int i = 0; i < 4; ++i) {
;                     u32x4 sw; sw.x = cvt_pk_bf16(S[2 * i][0], S[2 * i][1]); sw.y = cvt_pk_bf16(S[2 * i][2], S[2 * i][3]); sw.z = cvt_pk_bf16(S[2 * i + 1][0], S[2 * i + 1][1]); sw.w = cvt_pk_bf16(S[2 * i + 1][2], S[2 * i + 1][3]);
;                     u32x4 qw; qw.x = qlo[i][0]; qw.y = qlo[i][1]; qw.z = qhi[i][0]; qw.w = qhi[i][1];
;                     oacc = __builtin_amdgcn_mfma_f32_16x16x32_bf16(__builtin_bit_cast(bf16x8, sw), __builtin_bit_cast(bf16x8, qw), oacc, 0, 0, 0);
;                 }
;                 const LAS float* dv = (const LAS float*)(set + O_DV);
; #pragma unroll
;                 for (int kt = 0; kt < 8; ++kt) {
;                     const f32x4 d4 = *(const LAS f32x4*)(dv + kt * 16 + fq * 4);
;                     const bf16x8 ka = *(const LAS bf16x8*)(set + O_KD + (kt * 16 + fr) * 64 + fq * 16);
;                     S[kt] = __builtin_amdgcn_mfma_f32_16x16x32_bf16(ka, vf, S[kt] * d4, 0, 0, 0);
.LBB0_433:
	s_add_i32 s7, s6, 1
	s_bitcmp1_b32 s7, 0
	s_cselect_b32 s0, 0x8600, 0
	s_add_i32 s0, s0, 0
	v_lshl_add_u32 v1, v80, 2, s0
	v_lshl_add_u32 v0, v71, 2, v1
	ds_read2_b32 v[48:49], v0 offset1:132
	v_add_u32_e32 v3, 0x2000, v0
	ds_read2_b32 v[50:51], v3 offset0:64 offset1:196
	v_add_u32_e32 v3, 0x400, v0
	ds_read2_b32 v[98:99], v3 offset0:8 offset1:140
	v_add_u32_e32 v0, 0x2400, v0
	ds_read2_b32 v[100:101], v0 offset0:72 offset1:204
	s_waitcnt lgkmcnt(3)
	v_sub_f32_e32 v0, 1.0, v48
	v_max_f32_e32 v3, 0x3bdb8bac, v0
	v_sub_f32_e32 v0, 1.0, v49
	v_max_f32_e32 v0, 0x3bdb8bac, v0
	v_mul_f32_e32 v65, v3, v0
	s_waitcnt lgkmcnt(1)
	v_sub_f32_e32 v0, 1.0, v98
	v_max_f32_e32 v0, 0x3bdb8bac, v0
	v_mul_f32_e32 v104, v65, v0
	v_sub_f32_e32 v0, 1.0, v99
	v_max_f32_e32 v0, 0x3bdb8bac, v0
	v_mul_f32_e32 v105, v104, v0
	v_add3_u32 v1, v1, v90, v206
	s_nop 0
	v_mul_f32_dpp v0, v105, v105 quad_perm:[0,0,1,2] row_mask:0xf bank_mask:0xf bound_ctrl:1
	v_cndmask_b32_e64 v0, v0, v105, s[44:45]
	s_nop 1
	v_mul_f32_dpp v102, v0, v0 quad_perm:[0,0,0,1] row_mask:0xf bank_mask:0xf bound_ctrl:1
	v_cndmask_b32_e64 v102, v0, v102, s[46:47]
	v_mov_b32_e32 v0, 0
	s_nop 1
	v_mov_b32_dpp v0, v102 quad_perm:[0,0,1,2] row_mask:0xf bank_mask:0xf
	v_cndmask_b32_e64 v106, v0, 1.0, s[44:45]
	v_mov_b32_e32 v0, 0
	v_mul_f32_e32 v3, v3, v106
	s_nop 0
	v_mov_b32_dpp v0, v102 quad_perm:[3,3,3,3] row_mask:0xf bank_mask:0xf
	v_rcp_f32_e32 v102, v3
	v_mul_f32_e32 v3, v50, v3
	v_cvt_pk_bf16_f32 v3, v3, s0
	ds_write_b16 v1, v3 offset:16896
	v_mul_f32_e32 v3, v65, v106
	v_rcp_f32_e32 v103, v3
	v_mul_f32_e32 v3, v51, v3
	v_cvt_pk_bf16_f32 v3, v3, s0
	ds_write_b16 v1, v3 offset:17168
	v_mul_f32_e32 v3, v104, v106
	v_rcp_f32_e32 v50, v3
	s_waitcnt lgkmcnt(2)
	v_mul_f32_e32 v3, v100, v3
	v_cvt_pk_bf16_f32 v3, v3, s0
	ds_write_b16 v1, v3 offset:17440
	v_mul_f32_e32 v3, v105, v106
	v_rcp_f32_e32 v51, v3
	v_mul_f32_e32 v3, v101, v3
	v_cvt_pk_bf16_f32 v3, v3, s0
	v_pk_mul_f32 v[48:49], v[48:49], v[102:103]
	ds_write_b16 v1, v3 offset:17712
	v_cvt_pk_bf16_f32 v3, v48, s0
	ds_write_b16 v1, v3 offset:21248
	v_cvt_pk_bf16_f32 v3, v49, s0
	v_pk_mul_f32 v[50:51], v[98:99], v[50:51]
	ds_write_b16 v1, v3 offset:21520
	v_cvt_pk_bf16_f32 v3, v50, s0
	ds_write_b16 v1, v3 offset:21792
	v_cvt_pk_bf16_f32 v3, v51, s0
	v_pk_mul_f32 v[100:101], v[48:49], v[0:1] op_sel_hi:[1,0]
	v_pk_mul_f32 v[98:99], v[50:51], v[0:1] op_sel_hi:[1,0]
	ds_write_b16 v1, v3 offset:22064
	v_add_u32_e32 v1, s0, v83
	v_cvt_pk_bf16_f32 v48, v100, v101
	v_cvt_pk_bf16_f32 v49, v98, v99
	v_add_u32_e32 v3, v1, v55
	ds_write_b64 v3, v[48:49] offset:25600
	s_and_saveexec_b64 s[0:1], s[44:45]
	v_add_u32_e32 v1, v1, v84
	ds_write_b32 v1, v0 offset:33792
	s_or_b64 exec, exec, s[0:1]
	s_mul_hi_u32 s0, s6, 0xaaaaaaab
	s_lshr_b32 s0, s0, 1
	s_bitcmp1_b32 s6, 0
	s_cselect_b32 s1, 0x8600, 0
	s_add_i32 s14, s1, 0
	v_add_u32_e32 v0, s14, v88
	v_add_u32_e32 v1, v0, v89
	ds_read_b128 v[48:51], v1 offset:21248
	ds_read_b128 v[98:101], v1 offset:21312
	ds_read_b128 v[126:129], v1 offset:16896
	ds_read_b128 v[130:133], v1 offset:16960
	ds_read_b128 v[110:113], v1 offset:21376
	ds_read_b128 v[114:117], v1 offset:21440
	ds_read_b128 v[134:137], v1 offset:17024
	ds_read_b128 v[138:141], v1 offset:17088
	s_mulk_i32 s0, 0xa000
	v_add_u32_e32 v0, s0, v95
	ds_read_b128 v[142:145], v0
	s_setprio 1
	s_waitcnt lgkmcnt(6)
	v_mfma_f32_16x16x32_bf16 v[48:51], v[48:51], v[126:129], 0
	v_add_u32_e32 v0, s14, v89
	v_add_u32_e32 v1, v0, v210
	v_cvt_pk_bf16_f32 v146, v44, v45
	s_waitcnt lgkmcnt(5)
	v_mfma_f32_16x16x32_bf16 v[48:51], v[98:101], v[130:133], v[48:51]
	ds_read_b64 v[184:185], v1 offset:25600
	ds_read_b128 v[104:107], v0 offset:33792
	v_cvt_pk_bf16_f32 v147, v46, v47
	v_cvt_pk_bf16_f32 v148, v16, v17
	s_waitcnt lgkmcnt(4)
; #define LAS __attribute__((address_space(3)))
; __device__ __forceinline__ void scan_phase(LAS unsigned char* lds, bf16* proj, int G, int bid) {
;     ...
; #pragma unroll
;                 for (int kt = 0; kt < 8; ++kt) {
;                     const f32x4 d4 = *(const LAS f32x4*)(dv + kt * 16 + fq * 4);
;                     const bf16x8 ka = *(const LAS bf16x8*)(set + O_KD + (kt * 16 + fr) * 64 + fq * 16);
;                     S[kt] = __builtin_amdgcn_mfma_f32_16x16x32_bf16(ka, vf, S[kt] * d4, 0, 0, 0);
;                 }
; #pragma unroll
;                 for (int j = 0; j < 4; ++j) pt[j] = (fq * 4 + j <= fr) ? pt[j] : 0.f;
;                 u32x4 pw; pw.x = cvt_pk_bf16(pt[0], pt[1]); pw.y = cvt_pk_bf16(pt[2], pt[3]); pw.z = 0u; pw.w = 0u;
;                 oacc = __builtin_amdgcn_mfma_f32_16x16x32_bf16(vf, __builtin_bit_cast(bf16x8, pw), oacc, 0, 0, 0);
	v_mfma_f32_16x16x32_bf16 v[48:51], v[110:113], v[134:137], v[48:51]
	ds_read_b128 v[108:111], v0 offset:33856
	ds_read_b64 v[188:189], v1 offset:26624
	s_waitcnt lgkmcnt(2)
	v_pk_mul_f32 v[46:47], v[46:47], v[106:107]
	v_pk_mul_f32 v[44:45], v[44:45], v[104:105]
	ds_read_b64 v[232:233], v1 offset:32768
	s_waitcnt lgkmcnt(2)
	v_pk_mul_f32 v[16:17], v[16:17], v[108:109]
	v_mfma_f32_16x16x32_bf16 v[44:47], v[184:187], v[142:145], v[44:47]
	ds_read_b64 v[192:193], v1 offset:27648
	ds_read_b128 v[106:109], v0 offset:33920
	v_cvt_pk_bf16_f32 v149, v18, v19
	v_cvt_pk_bf16_f32 v150, v20, v21
	v_cvt_pk_bf16_f32 v151, v22, v23
	v_pk_mul_f32 v[18:19], v[18:19], v[110:111]
	s_waitcnt lgkmcnt(0)
	v_pk_mul_f32 v[22:23], v[22:23], v[108:109]
	v_pk_mul_f32 v[20:21], v[20:21], v[106:107]
	v_mfma_f32_16x16x32_bf16 v[16:19], v[188:191], v[142:145], v[16:19]
	ds_read_b128 v[110:113], v0 offset:33984
	ds_read_b64 v[196:197], v1 offset:28672
	v_cvt_pk_bf16_f32 v152, v24, v25
	v_cvt_pk_bf16_f32 v153, v26, v27
	v_mfma_f32_16x16x32_bf16 v[20:23], v[192:195], v[142:145], v[20:23]
	ds_read_b64 v[200:201], v1 offset:29696
	ds_read_b128 v[106:109], v0 offset:34048
	s_waitcnt lgkmcnt(3)
	v_pk_mul_f32 v[26:27], v[26:27], v[112:113]
	v_pk_mul_f32 v[24:25], v[24:25], v[110:111]
	v_cvt_pk_bf16_f32 v154, v28, v29
	v_cvt_pk_bf16_f32 v155, v30, v31
	s_waitcnt lgkmcnt(2)
	v_mfma_f32_16x16x32_bf16 v[24:27], v[196:199], v[142:145], v[24:27]
	ds_read_b64 v[224:225], v1 offset:30720
	ds_read_b128 v[118:121], v0 offset:34112
	s_waitcnt lgkmcnt(2)
	v_pk_mul_f32 v[30:31], v[30:31], v[108:109]
	v_pk_mul_f32 v[28:29], v[28:29], v[106:107]
	v_cvt_pk_bf16_f32 v156, v32, v33
	v_cvt_pk_bf16_f32 v157, v34, v35
	v_mfma_f32_16x16x32_bf16 v[28:31], v[200:203], v[142:145], v[28:31]
	ds_read_b128 v[98:101], v0 offset:34176
	s_waitcnt lgkmcnt(1)
	v_pk_mul_f32 v[34:35], v[34:35], v[120:121]
	v_pk_mul_f32 v[32:33], v[32:33], v[118:119]
	v_cvt_pk_bf16_f32 v102, v36, v37
	v_cvt_pk_bf16_f32 v103, v38, v39
	v_mfma_f32_16x16x32_bf16 v[32:35], v[224:227], v[142:145], v[32:35]
	ds_read_b128 v[110:113], v0 offset:34240
	s_waitcnt lgkmcnt(1)
	v_pk_mul_f32 v[38:39], v[38:39], v[100:101]
	v_pk_mul_f32 v[36:37], v[36:37], v[98:99]
	v_mfma_f32_16x16x32_bf16 v[98:101], v[146:149], v[126:129], 0
	v_cvt_pk_bf16_f32 v104, v40, v41
	ds_read_b64 v[228:229], v1 offset:31744
	v_cvt_pk_bf16_f32 v105, v42, v43
	v_mfma_f32_16x16x32_bf16 v[98:101], v[150:153], v[130:133], v[98:101]
	s_waitcnt lgkmcnt(1)
	v_pk_mul_f32 v[42:43], v[42:43], v[112:113]
	v_pk_mul_f32 v[40:41], v[40:41], v[110:111]
	v_mfma_f32_16x16x32_bf16 v[48:51], v[114:117], v[138:141], v[48:51]
	v_mfma_f32_16x16x32_bf16 v[98:101], v[154:157], v[134:137], v[98:101]
	v_mfma_f32_16x16x32_bf16 v[98:101], v[102:105], v[138:141], v[98:101]
	s_nop 5
	v_cvt_pk_bf16_f32 v0, v48, s0
	v_cvt_pk_bf16_f32 v1, v49, s0
	v_cndmask_b32_e64 v0, v0, 0, s[48:49]
	v_cndmask_b32_e64 v1, 0, v1, s[50:51]
	v_perm_b32 v0, v1, v0, s11
	v_cvt_pk_bf16_f32 v1, v50, s0
	v_cvt_pk_bf16_f32 v3, v51, s0
	v_cndmask_b32_e64 v1, v1, 0, s[52:53]
	v_cndmask_b32_e64 v3, v3, 0, s[54:55]
	v_perm_b32 v1, v3, v1, s11
	v_mov_b32_e32 v3, v2
	s_waitcnt lgkmcnt(0)
	v_mfma_f32_16x16x32_bf16 v[36:39], v[228:231], v[142:145], v[36:39]
	v_mfma_f32_16x16x32_bf16 v[40:43], v[232:235], v[142:145], v[40:43]
	v_mfma_f32_16x16x32_bf16 v[48:51], v[142:145], v[0:3], v[98:101]
	s_setprio 0
	s_mov_b64 s[0:1], -1
	s_cmp_gt_u32 s6, 15
	v_add_u32_e32 v1, s4, v53
	s_cbranch_scc0 .LBB0_437
	v_add_u32_e32 v0, 0xffffff00, v1
	v_cndmask_b32_e64 v0, v96, v0, s[56:57]
	v_add_u32_e32 v0, s5, v0
	s_mov_b64 s[0:1], 0
